# scan: one static s_setprio 2 for the recurrence waves (0-3) over the loader waves sharing their SIMDs, reset at exit
# speedup vs baseline: 1.0036x; 1.0036x over previous
; #define LAS __attribute__((address_space(3)))
; __device__ __forceinline__ float bf_lo(unsigned w) { return __uint_as_float(w << 16); }
; __device__ __forceinline__ float bf_hi(unsigned w) { return __uint_as_float(w & 0xffff0000u); }
; __device__ __forceinline__ int opaque_tid() { int t = threadIdx.x; asm volatile("" : "+v"(t)); return t; }
; __device__ __forceinline__ void rwkv_scan(const Params& p, LAS unsigned char* lds, int rowbase, int T, int h, int q4, const float* S0, float* Sout) {
;     const int tid = opaque_tid(), lane = tid & 63, w = __builtin_amdgcn_readfirstlane(tid >> 6), rowl = lane >> 4, seg = lane & 15; const int vloc = (w & 3) * 4 + rowl, vrow = q4 * 16 + vloc;
;     unsigned char* ws = p.ws;
;     const float* decay = p.out; const bf16_t* kk = (const bf16_t*)((const unsigned char*)p.out + 68157440); const bf16_t* kka = (const bf16_t*)((const unsigned char*)p.out + 68157440 + HALF512);
;     const bf16_t* kp = (const bf16_t*)(ws + WS_PRW); const bf16_t* rb = (const bf16_t*)(ws + WS_A); const bf16_t* vb = (const bf16_t*)(ws + WS_A + HALF512);
;     bf16_t* ob = (bf16_t*)(ws + WS_B);
;     const bool comp = w < 4;
;     f32x4 S = (f32x4){0.f, 0.f, 0.f, 0.f};
;     if (comp && S0) S = *(const f32x4*)(S0 + vrow * 64 + seg * 4);
;     constexpr int BUF = 43008;
;     const bool ldr = w >= 4; const int lt = tid & 255, lstep = lt >> 4, lj = lt & 15;
;     f32x4 gd[2]; u32x2 gk[2], ga[2], gp[2], gr[2], gv[2];
;     auto gload = [&](int c) {
;         if (ldr) {
; #pragma unroll
;             for (int q = 0; q < 2; ++q) {
;                 const size_t row = (size_t)(rowbase + c * 32 + lstep + q * 16); const size_t o = row * 512 + h * 64 + lj * 4;
;                 gd[q] = *(const f32x4*)(decay + o); gk[q] = *(const u32x2*)(kk + o); ga[q] = *(const u32x2*)(kka + o); gp[q] = *(const u32x2*)(kp + o); gr[q] = *(const u32x2*)(rb + o);
;                 gv[q] = *(const u32x2*)(vb + row * 512 + h * 64 + q4 * 16 + (lj & 3) * 4);
;             }
;         }
;     };
;     auto up4 = [](const u32x2 x) { return (f32x4){bf_lo(x.x), bf_hi(x.x), bf_lo(x.y), bf_hi(x.y)}; };
;     float selv[16];
; #pragma unroll
;     for (int i = 0; i < 16; ++i) selv[i] = (seg == i) ? 1.0f : 0.0f;
;     const int nch = T / 32;
;     gload(0);
; #pragma unroll 1
;     for (int c = 0; c < nch; ++c) {
;         LAS unsigned char* b = lds + (c & 1) * BUF;
.LBB0_757:
	v_lshrrev_b32_e32 v2, 6, v200
	s_and_b32 s47, s44, 7
	s_lshr_b32 s5, s44, 3
	s_lshl_b32 s47, s47, 3
	s_lshr_b32 s4, s5, 2
	s_add_i32 s47, s47, s4
	s_lshl_b32 s47, s47, 2
	s_and_b32 s5, s5, 3
	s_or_b32 s47, s47, s5
	s_bfe_u32 s45, s47, 0x30002
	s_ashr_i32 s33, s47, 5
	v_readfirstlane_b32 s46, v2
	s_lshl_b32 s42, s33, 12
	s_lshl_b32 s4, s47, 4
	s_and_b32 s43, s4, 48
	s_waitcnt vmcnt(0)
	s_mov_b32 s22, 0
	s_mov_b32 s38, 35328
	s_mov_b32 s39, 0xffff7600
	v_and_b32_e32 v0, 63, v200
	s_cmp_lt_i32 s46, 4
	s_cbranch_scc0 .Lrw3_loader
	s_setprio 2
	s_mov_b32 s98, 0xcccccccc
	s_mov_b32 s99, 0xcccccccc
	s_mov_b32 s100, 0xaaaaaaaa
	s_mov_b32 s101, 0xaaaaaaaa
	v_and_b32_e32 v196, 15, v0
	v_lshrrev_b32_e32 v194, 4, v0
	s_lshl_b32 s4, s46, 2
	v_add_u32_e32 v194, s4, v194
	v_lshlrev_b32_e32 v2, 4, v196
	v_mul_u32_u24_e32 v3, 144, v194
	v_add_u32_e32 v3, 32768, v3
	v_add_u32_e32 v4, 35072, v2
	v_add_u32_e32 v5, s42, v196
	v_add_u32_e32 v194, s43, v194
	s_lshl_b32 s4, s45, 7
	s_add_u32 s4, s18, s4
	s_addc_u32 s5, s19, 0
	v_lshlrev_b32_e32 v198, 1, v194
	v_mov_b32_e32 v199, 0
	v_lshl_add_u64 v[6:7], s[4:5], 0, v[198:199]
	s_lshl_b32 s4, s33, 3
	s_or_b32 s4, s4, s45
	s_lshl_b32 s4, s4, 14
	s_add_u32 s4, s15, s4
	s_addc_u32 s5, s35, 0
	v_lshlrev_b32_e32 v198, 8, v194
	v_lshl_add_u32 v198, v196, 4, v198
	v_lshl_add_u64 v[8:9], s[4:5], 0, v[198:199]
	v_mov_b32_e32 v12, 0
	v_mov_b32_e32 v13, 0
	v_mov_b32_e32 v14, 0
	v_mov_b32_e32 v15, 0
.Lrw3_cloop:
	s_barrier
	ds_read_b128 v[76:79], v2 offset:0
	ds_read_b128 v[84:87], v2 offset:16384
	ds_read_b128 v[80:83], v2 offset:8192
	ds_read_b128 v[124:127], v2 offset:24576
	ds_read_b128 v[24:27], v3 offset:0
	ds_read_b128 v[88:91], v2 offset:256
	ds_read_b128 v[96:99], v2 offset:16640
	ds_read_b128 v[92:95], v2 offset:8448
	ds_read_b128 v[128:131], v2 offset:24832
	ds_read_b128 v[100:103], v2 offset:512
	ds_read_b128 v[108:111], v2 offset:16896
	ds_read_b128 v[104:107], v2 offset:8704
	ds_read_b128 v[132:135], v2 offset:25088
	s_waitcnt lgkmcnt(5)
	v_pk_mul_f32 v[72:73], v[12:13], v[76:77]
	v_pk_fma_f32 v[72:73], v[14:15], v[78:79], v[72:73]
	ds_read_b128 v[112:115], v2 offset:768
	v_add_f32_e32 v74, v72, v73
	ds_read_b128 v[120:123], v2 offset:17152
	ds_read_b128 v[116:119], v2 offset:8960
	v_add_f32_dpp v74, v74, v74 quad_perm:[1,0,3,2] row_mask:0xf bank_mask:0xf bound_ctrl:1
	ds_read_b128 v[136:139], v2 offset:25344
	v_pk_fma_f32 v[16:17], v[24:25], v[84:85], v[12:13] op_sel_hi:[0,1,1]
	v_add_f32_dpp v74, v74, v74 quad_perm:[2,3,0,1] row_mask:0xf bank_mask:0xf bound_ctrl:1
	v_pk_fma_f32 v[18:19], v[24:25], v[86:87], v[14:15] op_sel_hi:[0,1,1]
	s_nop 0
	v_add_f32_dpp v74, v74, v74 row_half_mirror row_mask:0xf bank_mask:0xf bound_ctrl:1
	s_nop 1
	v_add_f32_dpp v74, v74, v74 row_mirror row_mask:0xf bank_mask:0xf bound_ctrl:1
	v_pk_fma_f32 v[12:13], v[80:81], v[74:75], v[16:17] op_sel_hi:[1,0,1] neg_lo:[0,1,0] neg_hi:[0,1,0]
	v_pk_fma_f32 v[14:15], v[82:83], v[74:75], v[18:19] op_sel_hi:[1,0,1] neg_lo:[0,1,0] neg_hi:[0,1,0]
	v_pk_mul_f32 v[72:73], v[12:13], v[88:89]
	v_pk_fma_f32 v[72:73], v[14:15], v[90:91], v[72:73]
	ds_read_b128 v[76:79], v2 offset:1024
	v_add_f32_e32 v74, v72, v73
	ds_read_b128 v[84:87], v2 offset:17408
	ds_read_b128 v[80:83], v2 offset:9216
	v_add_f32_dpp v74, v74, v74 quad_perm:[1,0,3,2] row_mask:0xf bank_mask:0xf bound_ctrl:1
	ds_read_b128 v[140:143], v2 offset:25600
	ds_read_b128 v[28:31], v3 offset:16
	v_add_f32_dpp v74, v74, v74 quad_perm:[2,3,0,1] row_mask:0xf bank_mask:0xf bound_ctrl:1
	v_pk_fma_f32 v[16:17], v[24:25], v[96:97], v[12:13] op_sel:[1,0,0] op_sel_hi:[1,1,1]
	v_pk_fma_f32 v[18:19], v[24:25], v[98:99], v[14:15] op_sel:[1,0,0] op_sel_hi:[1,1,1]
	v_add_f32_dpp v74, v74, v74 row_half_mirror row_mask:0xf bank_mask:0xf bound_ctrl:1
	v_pk_mul_f32 v[198:199], v[12:13], v[124:125]
	v_pk_fma_f32 v[198:199], v[14:15], v[126:127], v[198:199]
	v_add_f32_dpp v74, v74, v74 row_mirror row_mask:0xf bank_mask:0xf bound_ctrl:1
	v_add_f32_e32 v144, v198, v199
	v_pk_fma_f32 v[12:13], v[92:93], v[74:75], v[16:17] op_sel_hi:[1,0,1] neg_lo:[0,1,0] neg_hi:[0,1,0]
	v_pk_fma_f32 v[14:15], v[94:95], v[74:75], v[18:19] op_sel_hi:[1,0,1] neg_lo:[0,1,0] neg_hi:[0,1,0]
	s_waitcnt lgkmcnt(6)
	v_pk_mul_f32 v[72:73], v[12:13], v[100:101]
	v_pk_fma_f32 v[72:73], v[14:15], v[102:103], v[72:73]
	ds_read_b128 v[88:91], v2 offset:1280
	v_add_f32_e32 v74, v72, v73
	ds_read_b128 v[96:99], v2 offset:17664
	ds_read_b128 v[92:95], v2 offset:9472
	v_add_f32_dpp v74, v74, v74 quad_perm:[1,0,3,2] row_mask:0xf bank_mask:0xf bound_ctrl:1
	ds_read_b128 v[124:127], v2 offset:25856
	v_pk_fma_f32 v[16:17], v[26:27], v[108:109], v[12:13] op_sel_hi:[0,1,1]
	v_add_f32_dpp v74, v74, v74 quad_perm:[2,3,0,1] row_mask:0xf bank_mask:0xf bound_ctrl:1
	v_pk_fma_f32 v[18:19], v[26:27], v[110:111], v[14:15] op_sel_hi:[0,1,1]
	v_pk_mul_f32 v[198:199], v[12:13], v[128:129]
	v_add_f32_dpp v74, v74, v74 row_half_mirror row_mask:0xf bank_mask:0xf bound_ctrl:1
	v_pk_fma_f32 v[198:199], v[14:15], v[130:131], v[198:199]
	v_add_f32_e32 v145, v198, v199
	v_add_f32_dpp v74, v74, v74 row_mirror row_mask:0xf bank_mask:0xf bound_ctrl:1
	v_pk_fma_f32 v[12:13], v[104:105], v[74:75], v[16:17] op_sel_hi:[1,0,1] neg_lo:[0,1,0] neg_hi:[0,1,0]
	v_pk_fma_f32 v[14:15], v[106:107], v[74:75], v[18:19] op_sel_hi:[1,0,1] neg_lo:[0,1,0] neg_hi:[0,1,0]
	v_pk_mul_f32 v[72:73], v[12:13], v[112:113]
	v_pk_fma_f32 v[72:73], v[14:15], v[114:115], v[72:73]
	ds_read_b128 v[100:103], v2 offset:1536
	v_add_f32_e32 v74, v72, v73
	ds_read_b128 v[108:111], v2 offset:17920
	ds_read_b128 v[104:107], v2 offset:9728
	v_add_f32_dpp v74, v74, v74 quad_perm:[1,0,3,2] row_mask:0xf bank_mask:0xf bound_ctrl:1
	ds_read_b128 v[128:131], v2 offset:26112
	v_pk_fma_f32 v[16:17], v[26:27], v[120:121], v[12:13] op_sel:[1,0,0] op_sel_hi:[1,1,1]
	v_add_f32_dpp v74, v74, v74 quad_perm:[2,3,0,1] row_mask:0xf bank_mask:0xf bound_ctrl:1
	v_pk_fma_f32 v[18:19], v[26:27], v[122:123], v[14:15] op_sel:[1,0,0] op_sel_hi:[1,1,1]
	v_pk_mul_f32 v[198:199], v[12:13], v[132:133]
	v_add_f32_dpp v74, v74, v74 row_half_mirror row_mask:0xf bank_mask:0xf bound_ctrl:1
	v_pk_fma_f32 v[198:199], v[14:15], v[134:135], v[198:199]
	v_add_f32_e32 v146, v198, v199
	v_add_f32_dpp v74, v74, v74 row_mirror row_mask:0xf bank_mask:0xf bound_ctrl:1
	v_pk_fma_f32 v[12:13], v[116:117], v[74:75], v[16:17] op_sel_hi:[1,0,1] neg_lo:[0,1,0] neg_hi:[0,1,0]
	v_pk_fma_f32 v[14:15], v[118:119], v[74:75], v[18:19] op_sel_hi:[1,0,1] neg_lo:[0,1,0] neg_hi:[0,1,0]
	s_waitcnt lgkmcnt(5)
; #define RW_LD(X, s) do { X.d = *(const LAS f32x4*)(bs + (s) * 256); X.k = *(const LAS f32x4*)(bs + 8192 + (s) * 256); X.a = *(const LAS f32x4*)(bs + 16384 + (s) * 256); \
;                          X.p = *(const LAS f32x4*)(bs + 24576 + (s) * 256); X.r = *(const LAS f32x4*)(bs + 32768 + (s) * 256); X.v = *(const LAS float*)(bv + (s) * 64); } while (0)
; #define RW_STEP(X, s) do { float sa = fmaf(S[3], X.k[3], fmaf(S[2], X.k[2], fmaf(S[1], X.k[1], S[0] * X.k[0]))); const f32x4 T = S * X.d + X.v * X.p; sa = -red16(sa); \
;                            S = T + sa * X.a; float y = fmaf(S[3], X.r[3], fmaf(S[2], X.r[2], fmaf(S[1], X.r[1], S[0] * X.r[0]))); y = red16(y); \
;                            yk = fmaf(selv[(s) & 15], y, yk); } while (0)
; #define RW_YST(s) do { if ((s) == 15) { ob[(size_t)(rowbase + c * 32 + seg) * D + 512 + h * 64 + vrow] = f2bf(yk); yk = 0.f; } } while (0)
; __device__ __forceinline__ void rwkv_scan(const Params& p, LAS unsigned char* lds, int rowbase, int T, int h, int q4, const float* S0, float* Sout) {
;     ...
;             RwStep xa, xb, xc; float yk = 0.f;
;     ...
;             RW_LD(xa, 0); RW_LD(xb, 1);
; #pragma unroll
;             for (int s = 0; s < 30; s += 3) {
;                 RW_LD(xc, s + 2); RW_STEP(xa, s); RW_YST(s);
;                 RW_LD(xa, s + 3); RW_STEP(xb, s + 1); RW_YST(s + 1);
;                 RW_LD(xb, s + 4); RW_STEP(xc, s + 2); RW_YST(s + 2);
;             }
	v_pk_mul_f32 v[72:73], v[12:13], v[76:77]
	v_pk_fma_f32 v[72:73], v[14:15], v[78:79], v[72:73]
	ds_read_b128 v[112:115], v2 offset:1792
	v_add_f32_e32 v74, v72, v73
	ds_read_b128 v[120:123], v2 offset:18176
	ds_read_b128 v[116:119], v2 offset:9984
	v_add_f32_dpp v74, v74, v74 quad_perm:[1,0,3,2] row_mask:0xf bank_mask:0xf bound_ctrl:1
	ds_read_b128 v[132:135], v2 offset:26368
	v_pk_fma_f32 v[16:17], v[28:29], v[84:85], v[12:13] op_sel_hi:[0,1,1]
	v_add_f32_dpp v74, v74, v74 quad_perm:[2,3,0,1] row_mask:0xf bank_mask:0xf bound_ctrl:1
	v_pk_fma_f32 v[18:19], v[28:29], v[86:87], v[14:15] op_sel_hi:[0,1,1]
	v_pk_mul_f32 v[198:199], v[12:13], v[136:137]
	v_add_f32_dpp v74, v74, v74 row_half_mirror row_mask:0xf bank_mask:0xf bound_ctrl:1
	v_pk_fma_f32 v[198:199], v[14:15], v[138:139], v[198:199]
	v_add_f32_e32 v147, v198, v199
	v_add_f32_dpp v74, v74, v74 row_mirror row_mask:0xf bank_mask:0xf bound_ctrl:1
	v_pk_fma_f32 v[12:13], v[80:81], v[74:75], v[16:17] op_sel_hi:[1,0,1] neg_lo:[0,1,0] neg_hi:[0,1,0]
	v_pk_fma_f32 v[14:15], v[82:83], v[74:75], v[18:19] op_sel_hi:[1,0,1] neg_lo:[0,1,0] neg_hi:[0,1,0]
	v_pk_mul_f32 v[72:73], v[12:13], v[88:89]
	v_pk_fma_f32 v[72:73], v[14:15], v[90:91], v[72:73]
	ds_read_b128 v[76:79], v2 offset:2048
	v_add_f32_e32 v74, v72, v73
	ds_read_b128 v[84:87], v2 offset:18432
	ds_read_b128 v[80:83], v2 offset:10240
	v_add_f32_dpp v74, v74, v74 quad_perm:[1,0,3,2] row_mask:0xf bank_mask:0xf bound_ctrl:1
	ds_read_b128 v[136:139], v2 offset:26624
	ds_read_b128 v[24:27], v3 offset:32
	v_add_f32_dpp v74, v74, v74 quad_perm:[2,3,0,1] row_mask:0xf bank_mask:0xf bound_ctrl:1
	v_pk_fma_f32 v[16:17], v[28:29], v[96:97], v[12:13] op_sel:[1,0,0] op_sel_hi:[1,1,1]
	v_pk_fma_f32 v[18:19], v[28:29], v[98:99], v[14:15] op_sel:[1,0,0] op_sel_hi:[1,1,1]
	v_add_f32_dpp v74, v74, v74 row_half_mirror row_mask:0xf bank_mask:0xf bound_ctrl:1
	v_pk_mul_f32 v[198:199], v[12:13], v[140:141]
	v_pk_fma_f32 v[198:199], v[14:15], v[142:143], v[198:199]
	v_add_f32_dpp v74, v74, v74 row_mirror row_mask:0xf bank_mask:0xf bound_ctrl:1
	v_add_f32_e32 v148, v198, v199
	v_pk_fma_f32 v[12:13], v[92:93], v[74:75], v[16:17] op_sel_hi:[1,0,1] neg_lo:[0,1,0] neg_hi:[0,1,0]
	v_pk_fma_f32 v[14:15], v[94:95], v[74:75], v[18:19] op_sel_hi:[1,0,1] neg_lo:[0,1,0] neg_hi:[0,1,0]
	s_waitcnt lgkmcnt(6)
	v_pk_mul_f32 v[72:73], v[12:13], v[100:101]
	v_pk_fma_f32 v[72:73], v[14:15], v[102:103], v[72:73]
	ds_read_b128 v[88:91], v2 offset:2304
	v_add_f32_e32 v74, v72, v73
	ds_read_b128 v[96:99], v2 offset:18688
	ds_read_b128 v[92:95], v2 offset:10496
	v_add_f32_dpp v74, v74, v74 quad_perm:[1,0,3,2] row_mask:0xf bank_mask:0xf bound_ctrl:1
	ds_read_b128 v[140:143], v2 offset:26880
	v_pk_fma_f32 v[16:17], v[30:31], v[108:109], v[12:13] op_sel_hi:[0,1,1]
	v_add_f32_dpp v74, v74, v74 quad_perm:[2,3,0,1] row_mask:0xf bank_mask:0xf bound_ctrl:1
	v_pk_fma_f32 v[18:19], v[30:31], v[110:111], v[14:15] op_sel_hi:[0,1,1]
	v_pk_mul_f32 v[198:199], v[12:13], v[124:125]
	v_add_f32_dpp v74, v74, v74 row_half_mirror row_mask:0xf bank_mask:0xf bound_ctrl:1
	v_pk_fma_f32 v[198:199], v[14:15], v[126:127], v[198:199]
	v_add_f32_e32 v149, v198, v199
	v_add_f32_dpp v74, v74, v74 row_mirror row_mask:0xf bank_mask:0xf bound_ctrl:1
	v_pk_fma_f32 v[12:13], v[104:105], v[74:75], v[16:17] op_sel_hi:[1,0,1] neg_lo:[0,1,0] neg_hi:[0,1,0]
	v_pk_fma_f32 v[14:15], v[106:107], v[74:75], v[18:19] op_sel_hi:[1,0,1] neg_lo:[0,1,0] neg_hi:[0,1,0]
	v_pk_mul_f32 v[72:73], v[12:13], v[112:113]
	v_pk_fma_f32 v[72:73], v[14:15], v[114:115], v[72:73]
	ds_read_b128 v[100:103], v2 offset:2560
	v_add_f32_e32 v74, v72, v73
	ds_read_b128 v[108:111], v2 offset:18944
	ds_read_b128 v[104:107], v2 offset:10752
	v_add_f32_dpp v74, v74, v74 quad_perm:[1,0,3,2] row_mask:0xf bank_mask:0xf bound_ctrl:1
	ds_read_b128 v[124:127], v2 offset:27136
	v_pk_fma_f32 v[16:17], v[30:31], v[120:121], v[12:13] op_sel:[1,0,0] op_sel_hi:[1,1,1]
	v_add_f32_dpp v74, v74, v74 quad_perm:[2,3,0,1] row_mask:0xf bank_mask:0xf bound_ctrl:1
	v_pk_fma_f32 v[18:19], v[30:31], v[122:123], v[14:15] op_sel:[1,0,0] op_sel_hi:[1,1,1]
	v_pk_mul_f32 v[198:199], v[12:13], v[128:129]
	v_add_f32_dpp v74, v74, v74 row_half_mirror row_mask:0xf bank_mask:0xf bound_ctrl:1
	v_pk_fma_f32 v[198:199], v[14:15], v[130:131], v[198:199]
	v_add_f32_e32 v150, v198, v199
	v_add_f32_dpp v74, v74, v74 row_mirror row_mask:0xf bank_mask:0xf bound_ctrl:1
	v_pk_fma_f32 v[12:13], v[116:117], v[74:75], v[16:17] op_sel_hi:[1,0,1] neg_lo:[0,1,0] neg_hi:[0,1,0]
	v_pk_fma_f32 v[14:15], v[118:119], v[74:75], v[18:19] op_sel_hi:[1,0,1] neg_lo:[0,1,0] neg_hi:[0,1,0]
	s_waitcnt lgkmcnt(5)
; #define RW_LD(X, s) do { X.d = *(const LAS f32x4*)(bs + (s) * 256); X.k = *(const LAS f32x4*)(bs + 8192 + (s) * 256); X.a = *(const LAS f32x4*)(bs + 16384 + (s) * 256); \
;                          X.p = *(const LAS f32x4*)(bs + 24576 + (s) * 256); X.r = *(const LAS f32x4*)(bs + 32768 + (s) * 256); X.v = *(const LAS float*)(bv + (s) * 64); } while (0)
; #define RW_STEP(X, s) do { float sa = fmaf(S[3], X.k[3], fmaf(S[2], X.k[2], fmaf(S[1], X.k[1], S[0] * X.k[0]))); const f32x4 T = S * X.d + X.v * X.p; sa = -red16(sa); \
;                            S = T + sa * X.a; float y = fmaf(S[3], X.r[3], fmaf(S[2], X.r[2], fmaf(S[1], X.r[1], S[0] * X.r[0]))); y = red16(y); \
;                            yk = fmaf(selv[(s) & 15], y, yk); } while (0)
; #define RW_YST(s) do { if ((s) == 15) { ob[(size_t)(rowbase + c * 32 + seg) * D + 512 + h * 64 + vrow] = f2bf(yk); yk = 0.f; } } while (0)
; __device__ __forceinline__ void rwkv_scan(const Params& p, LAS unsigned char* lds, int rowbase, int T, int h, int q4, const float* S0, float* Sout) {
;     ...
;             RwStep xa, xb, xc; float yk = 0.f;
;     ...
;             RW_LD(xa, 0); RW_LD(xb, 1);
; #pragma unroll
;             for (int s = 0; s < 30; s += 3) {
;                 RW_LD(xc, s + 2); RW_STEP(xa, s); RW_YST(s);
;                 RW_LD(xa, s + 3); RW_STEP(xb, s + 1); RW_YST(s + 1);
;                 RW_LD(xb, s + 4); RW_STEP(xc, s + 2); RW_YST(s + 2);
;             }
	v_pk_mul_f32 v[72:73], v[12:13], v[76:77]
	v_pk_fma_f32 v[72:73], v[14:15], v[78:79], v[72:73]
	ds_read_b128 v[112:115], v2 offset:2816
	v_add_f32_e32 v74, v72, v73
	ds_read_b128 v[120:123], v2 offset:19200
	ds_read_b128 v[116:119], v2 offset:11008
	v_add_f32_dpp v74, v74, v74 quad_perm:[1,0,3,2] row_mask:0xf bank_mask:0xf bound_ctrl:1
	ds_read_b128 v[128:131], v2 offset:27392
	v_pk_fma_f32 v[16:17], v[24:25], v[84:85], v[12:13] op_sel_hi:[0,1,1]
	v_add_f32_dpp v74, v74, v74 quad_perm:[2,3,0,1] row_mask:0xf bank_mask:0xf bound_ctrl:1
	v_pk_fma_f32 v[18:19], v[24:25], v[86:87], v[14:15] op_sel_hi:[0,1,1]
	v_pk_mul_f32 v[198:199], v[12:13], v[132:133]
	v_add_f32_dpp v74, v74, v74 row_half_mirror row_mask:0xf bank_mask:0xf bound_ctrl:1
	v_pk_fma_f32 v[198:199], v[14:15], v[134:135], v[198:199]
	v_add_f32_e32 v151, v198, v199
	v_add_f32_dpp v74, v74, v74 row_mirror row_mask:0xf bank_mask:0xf bound_ctrl:1
	v_pk_fma_f32 v[12:13], v[80:81], v[74:75], v[16:17] op_sel_hi:[1,0,1] neg_lo:[0,1,0] neg_hi:[0,1,0]
	v_pk_fma_f32 v[14:15], v[82:83], v[74:75], v[18:19] op_sel_hi:[1,0,1] neg_lo:[0,1,0] neg_hi:[0,1,0]
	v_pk_mul_f32 v[72:73], v[12:13], v[88:89]
	v_pk_fma_f32 v[72:73], v[14:15], v[90:91], v[72:73]
	ds_read_b128 v[76:79], v2 offset:3072
	v_add_f32_e32 v74, v72, v73
	ds_read_b128 v[84:87], v2 offset:19456
	ds_read_b128 v[80:83], v2 offset:11264
	v_add_f32_dpp v74, v74, v74 quad_perm:[1,0,3,2] row_mask:0xf bank_mask:0xf bound_ctrl:1
	ds_read_b128 v[132:135], v2 offset:27648
	ds_read_b128 v[28:31], v3 offset:48
	v_add_f32_dpp v74, v74, v74 quad_perm:[2,3,0,1] row_mask:0xf bank_mask:0xf bound_ctrl:1
	v_pk_fma_f32 v[16:17], v[24:25], v[96:97], v[12:13] op_sel:[1,0,0] op_sel_hi:[1,1,1]
	v_pk_fma_f32 v[18:19], v[24:25], v[98:99], v[14:15] op_sel:[1,0,0] op_sel_hi:[1,1,1]
	v_add_f32_dpp v74, v74, v74 row_half_mirror row_mask:0xf bank_mask:0xf bound_ctrl:1
	v_pk_mul_f32 v[198:199], v[12:13], v[136:137]
	v_pk_fma_f32 v[198:199], v[14:15], v[138:139], v[198:199]
	v_add_f32_dpp v74, v74, v74 row_mirror row_mask:0xf bank_mask:0xf bound_ctrl:1
	v_add_f32_e32 v152, v198, v199
	v_pk_fma_f32 v[12:13], v[92:93], v[74:75], v[16:17] op_sel_hi:[1,0,1] neg_lo:[0,1,0] neg_hi:[0,1,0]
	v_pk_fma_f32 v[14:15], v[94:95], v[74:75], v[18:19] op_sel_hi:[1,0,1] neg_lo:[0,1,0] neg_hi:[0,1,0]
	v_add_f32_dpp v176, v144, v144 row_mirror row_mask:0xf bank_mask:0x3
	s_waitcnt lgkmcnt(6)
	v_pk_mul_f32 v[72:73], v[12:13], v[100:101]
	v_add_f32_dpp v176, v152, v152 row_mirror row_mask:0xf bank_mask:0xc
	v_pk_fma_f32 v[72:73], v[14:15], v[102:103], v[72:73]
	ds_read_b128 v[88:91], v2 offset:3328
	v_add_f32_e32 v74, v72, v73
	ds_read_b128 v[96:99], v2 offset:19712
	ds_read_b128 v[92:95], v2 offset:11520
	v_add_f32_dpp v74, v74, v74 quad_perm:[1,0,3,2] row_mask:0xf bank_mask:0xf bound_ctrl:1
	ds_read_b128 v[136:139], v2 offset:27904
	v_pk_fma_f32 v[16:17], v[26:27], v[108:109], v[12:13] op_sel_hi:[0,1,1]
	v_add_f32_dpp v74, v74, v74 quad_perm:[2,3,0,1] row_mask:0xf bank_mask:0xf bound_ctrl:1
	v_pk_fma_f32 v[18:19], v[26:27], v[110:111], v[14:15] op_sel_hi:[0,1,1]
	v_pk_mul_f32 v[198:199], v[12:13], v[140:141]
	v_add_f32_dpp v74, v74, v74 row_half_mirror row_mask:0xf bank_mask:0xf bound_ctrl:1
	v_pk_fma_f32 v[198:199], v[14:15], v[142:143], v[198:199]
	v_add_f32_e32 v153, v198, v199
	v_add_f32_dpp v74, v74, v74 row_mirror row_mask:0xf bank_mask:0xf bound_ctrl:1
	v_pk_fma_f32 v[12:13], v[104:105], v[74:75], v[16:17] op_sel_hi:[1,0,1] neg_lo:[0,1,0] neg_hi:[0,1,0]
	v_pk_fma_f32 v[14:15], v[106:107], v[74:75], v[18:19] op_sel_hi:[1,0,1] neg_lo:[0,1,0] neg_hi:[0,1,0]
	v_add_f32_dpp v177, v145, v145 row_mirror row_mask:0xf bank_mask:0x3
	v_pk_mul_f32 v[72:73], v[12:13], v[112:113]
	v_pk_fma_f32 v[72:73], v[14:15], v[114:115], v[72:73]
	v_add_f32_dpp v177, v153, v153 row_mirror row_mask:0xf bank_mask:0xc
	ds_read_b128 v[100:103], v2 offset:3584
	v_add_f32_e32 v74, v72, v73
	ds_read_b128 v[108:111], v2 offset:19968
	ds_read_b128 v[104:107], v2 offset:11776
	v_add_f32_dpp v74, v74, v74 quad_perm:[1,0,3,2] row_mask:0xf bank_mask:0xf bound_ctrl:1
	ds_read_b128 v[140:143], v2 offset:28160
	v_pk_fma_f32 v[16:17], v[26:27], v[120:121], v[12:13] op_sel:[1,0,0] op_sel_hi:[1,1,1]
	v_add_f32_dpp v74, v74, v74 quad_perm:[2,3,0,1] row_mask:0xf bank_mask:0xf bound_ctrl:1
	v_pk_fma_f32 v[18:19], v[26:27], v[122:123], v[14:15] op_sel:[1,0,0] op_sel_hi:[1,1,1]
	v_pk_mul_f32 v[198:199], v[12:13], v[124:125]
	v_add_f32_dpp v74, v74, v74 row_half_mirror row_mask:0xf bank_mask:0xf bound_ctrl:1
	v_pk_fma_f32 v[198:199], v[14:15], v[126:127], v[198:199]
	v_add_f32_e32 v154, v198, v199
	v_add_f32_dpp v74, v74, v74 row_mirror row_mask:0xf bank_mask:0xf bound_ctrl:1
	v_pk_fma_f32 v[12:13], v[116:117], v[74:75], v[16:17] op_sel_hi:[1,0,1] neg_lo:[0,1,0] neg_hi:[0,1,0]
	v_pk_fma_f32 v[14:15], v[118:119], v[74:75], v[18:19] op_sel_hi:[1,0,1] neg_lo:[0,1,0] neg_hi:[0,1,0]
	v_add_f32_dpp v178, v146, v146 row_mirror row_mask:0xf bank_mask:0x3
	s_waitcnt lgkmcnt(5)
; #define RW_LD(X, s) do { X.d = *(const LAS f32x4*)(bs + (s) * 256); X.k = *(const LAS f32x4*)(bs + 8192 + (s) * 256); X.a = *(const LAS f32x4*)(bs + 16384 + (s) * 256); \
;                          X.p = *(const LAS f32x4*)(bs + 24576 + (s) * 256); X.r = *(const LAS f32x4*)(bs + 32768 + (s) * 256); X.v = *(const LAS float*)(bv + (s) * 64); } while (0)
; #define RW_STEP(X, s) do { float sa = fmaf(S[3], X.k[3], fmaf(S[2], X.k[2], fmaf(S[1], X.k[1], S[0] * X.k[0]))); const f32x4 T = S * X.d + X.v * X.p; sa = -red16(sa); \
;                            S = T + sa * X.a; float y = fmaf(S[3], X.r[3], fmaf(S[2], X.r[2], fmaf(S[1], X.r[1], S[0] * X.r[0]))); y = red16(y); \
;                            yk = fmaf(selv[(s) & 15], y, yk); } while (0)
; #define RW_YST(s) do { if ((s) == 15) { ob[(size_t)(rowbase + c * 32 + seg) * D + 512 + h * 64 + vrow] = f2bf(yk); yk = 0.f; } } while (0)
; __device__ __forceinline__ void rwkv_scan(const Params& p, LAS unsigned char* lds, int rowbase, int T, int h, int q4, const float* S0, float* Sout) {
;     ...
;             RwStep xa, xb, xc; float yk = 0.f;
;     ...
;             RW_LD(xa, 0); RW_LD(xb, 1);
; #pragma unroll
;             for (int s = 0; s < 30; s += 3) {
;                 RW_LD(xc, s + 2); RW_STEP(xa, s); RW_YST(s);
;                 RW_LD(xa, s + 3); RW_STEP(xb, s + 1); RW_YST(s + 1);
;                 RW_LD(xb, s + 4); RW_STEP(xc, s + 2); RW_YST(s + 2);
;             }
	v_pk_mul_f32 v[72:73], v[12:13], v[76:77]
	v_add_f32_dpp v178, v154, v154 row_mirror row_mask:0xf bank_mask:0xc
	v_pk_fma_f32 v[72:73], v[14:15], v[78:79], v[72:73]
	ds_read_b128 v[112:115], v2 offset:3840
	v_add_f32_e32 v74, v72, v73
	ds_read_b128 v[120:123], v2 offset:20224
	ds_read_b128 v[116:119], v2 offset:12032
	v_add_f32_dpp v74, v74, v74 quad_perm:[1,0,3,2] row_mask:0xf bank_mask:0xf bound_ctrl:1
	ds_read_b128 v[124:127], v2 offset:28416
	v_pk_fma_f32 v[16:17], v[28:29], v[84:85], v[12:13] op_sel_hi:[0,1,1]
	v_add_f32_dpp v74, v74, v74 quad_perm:[2,3,0,1] row_mask:0xf bank_mask:0xf bound_ctrl:1
	v_pk_fma_f32 v[18:19], v[28:29], v[86:87], v[14:15] op_sel_hi:[0,1,1]
	v_pk_mul_f32 v[198:199], v[12:13], v[128:129]
	v_add_f32_dpp v74, v74, v74 row_half_mirror row_mask:0xf bank_mask:0xf bound_ctrl:1
	v_pk_fma_f32 v[198:199], v[14:15], v[130:131], v[198:199]
	v_add_f32_e32 v155, v198, v199
	v_add_f32_dpp v74, v74, v74 row_mirror row_mask:0xf bank_mask:0xf bound_ctrl:1
	v_pk_fma_f32 v[12:13], v[80:81], v[74:75], v[16:17] op_sel_hi:[1,0,1] neg_lo:[0,1,0] neg_hi:[0,1,0]
	v_pk_fma_f32 v[14:15], v[82:83], v[74:75], v[18:19] op_sel_hi:[1,0,1] neg_lo:[0,1,0] neg_hi:[0,1,0]
	v_add_f32_dpp v179, v147, v147 row_mirror row_mask:0xf bank_mask:0x3
	v_pk_mul_f32 v[72:73], v[12:13], v[88:89]
	v_pk_fma_f32 v[72:73], v[14:15], v[90:91], v[72:73]
	v_add_f32_dpp v179, v155, v155 row_mirror row_mask:0xf bank_mask:0xc
	ds_read_b128 v[76:79], v2 offset:4096
	v_add_f32_e32 v74, v72, v73
	ds_read_b128 v[84:87], v2 offset:20480
	ds_read_b128 v[80:83], v2 offset:12288
	v_add_f32_dpp v74, v74, v74 quad_perm:[1,0,3,2] row_mask:0xf bank_mask:0xf bound_ctrl:1
	ds_read_b128 v[128:131], v2 offset:28672
	ds_read_b128 v[24:27], v3 offset:64
	v_add_f32_dpp v74, v74, v74 quad_perm:[2,3,0,1] row_mask:0xf bank_mask:0xf bound_ctrl:1
	v_pk_fma_f32 v[16:17], v[28:29], v[96:97], v[12:13] op_sel:[1,0,0] op_sel_hi:[1,1,1]
	v_pk_fma_f32 v[18:19], v[28:29], v[98:99], v[14:15] op_sel:[1,0,0] op_sel_hi:[1,1,1]
	v_add_f32_dpp v74, v74, v74 row_half_mirror row_mask:0xf bank_mask:0xf bound_ctrl:1
	v_pk_mul_f32 v[198:199], v[12:13], v[132:133]
	v_pk_fma_f32 v[198:199], v[14:15], v[134:135], v[198:199]
	v_add_f32_dpp v74, v74, v74 row_mirror row_mask:0xf bank_mask:0xf bound_ctrl:1
	v_add_f32_e32 v156, v198, v199
	v_pk_fma_f32 v[12:13], v[92:93], v[74:75], v[16:17] op_sel_hi:[1,0,1] neg_lo:[0,1,0] neg_hi:[0,1,0]
	v_pk_fma_f32 v[14:15], v[94:95], v[74:75], v[18:19] op_sel_hi:[1,0,1] neg_lo:[0,1,0] neg_hi:[0,1,0]
	v_add_f32_dpp v180, v148, v148 row_mirror row_mask:0xf bank_mask:0x3
	s_waitcnt lgkmcnt(6)
	v_pk_mul_f32 v[72:73], v[12:13], v[100:101]
	v_add_f32_dpp v180, v156, v156 row_mirror row_mask:0xf bank_mask:0xc
	v_pk_fma_f32 v[72:73], v[14:15], v[102:103], v[72:73]
	ds_read_b128 v[88:91], v2 offset:4352
	v_add_f32_e32 v74, v72, v73
	ds_read_b128 v[96:99], v2 offset:20736
	ds_read_b128 v[92:95], v2 offset:12544
	v_add_f32_dpp v74, v74, v74 quad_perm:[1,0,3,2] row_mask:0xf bank_mask:0xf bound_ctrl:1
	ds_read_b128 v[132:135], v2 offset:28928
	v_pk_fma_f32 v[16:17], v[30:31], v[108:109], v[12:13] op_sel_hi:[0,1,1]
	v_add_f32_dpp v74, v74, v74 quad_perm:[2,3,0,1] row_mask:0xf bank_mask:0xf bound_ctrl:1
	v_pk_fma_f32 v[18:19], v[30:31], v[110:111], v[14:15] op_sel_hi:[0,1,1]
	v_pk_mul_f32 v[198:199], v[12:13], v[136:137]
	v_add_f32_dpp v74, v74, v74 row_half_mirror row_mask:0xf bank_mask:0xf bound_ctrl:1
	v_pk_fma_f32 v[198:199], v[14:15], v[138:139], v[198:199]
	v_add_f32_e32 v157, v198, v199
	v_add_f32_dpp v74, v74, v74 row_mirror row_mask:0xf bank_mask:0xf bound_ctrl:1
	v_pk_fma_f32 v[12:13], v[104:105], v[74:75], v[16:17] op_sel_hi:[1,0,1] neg_lo:[0,1,0] neg_hi:[0,1,0]
	v_pk_fma_f32 v[14:15], v[106:107], v[74:75], v[18:19] op_sel_hi:[1,0,1] neg_lo:[0,1,0] neg_hi:[0,1,0]
	v_add_f32_dpp v184, v176, v176 row_half_mirror row_mask:0xf bank_mask:0x5
	v_pk_mul_f32 v[72:73], v[12:13], v[112:113]
	v_pk_fma_f32 v[72:73], v[14:15], v[114:115], v[72:73]
	v_add_f32_dpp v184, v180, v180 row_half_mirror row_mask:0xf bank_mask:0xa
	ds_read_b128 v[100:103], v2 offset:4608
	v_add_f32_e32 v74, v72, v73
	ds_read_b128 v[108:111], v2 offset:20992
	ds_read_b128 v[104:107], v2 offset:12800
	v_add_f32_dpp v74, v74, v74 quad_perm:[1,0,3,2] row_mask:0xf bank_mask:0xf bound_ctrl:1
	ds_read_b128 v[136:139], v2 offset:29184
	v_pk_fma_f32 v[16:17], v[30:31], v[120:121], v[12:13] op_sel:[1,0,0] op_sel_hi:[1,1,1]
	v_add_f32_dpp v74, v74, v74 quad_perm:[2,3,0,1] row_mask:0xf bank_mask:0xf bound_ctrl:1
	v_pk_fma_f32 v[18:19], v[30:31], v[122:123], v[14:15] op_sel:[1,0,0] op_sel_hi:[1,1,1]
	v_pk_mul_f32 v[198:199], v[12:13], v[140:141]
	v_add_f32_dpp v74, v74, v74 row_half_mirror row_mask:0xf bank_mask:0xf bound_ctrl:1
	v_pk_fma_f32 v[198:199], v[14:15], v[142:143], v[198:199]
	v_add_f32_e32 v158, v198, v199
	v_add_f32_dpp v74, v74, v74 row_mirror row_mask:0xf bank_mask:0xf bound_ctrl:1
	v_pk_fma_f32 v[12:13], v[116:117], v[74:75], v[16:17] op_sel_hi:[1,0,1] neg_lo:[0,1,0] neg_hi:[0,1,0]
	v_pk_fma_f32 v[14:15], v[118:119], v[74:75], v[18:19] op_sel_hi:[1,0,1] neg_lo:[0,1,0] neg_hi:[0,1,0]
	v_add_f32_dpp v181, v149, v149 row_mirror row_mask:0xf bank_mask:0x3
	v_add_f32_dpp v185, v177, v177 row_half_mirror row_mask:0xf bank_mask:0x5
	s_waitcnt lgkmcnt(5)
; #define RW_LD(X, s) do { X.d = *(const LAS f32x4*)(bs + (s) * 256); X.k = *(const LAS f32x4*)(bs + 8192 + (s) * 256); X.a = *(const LAS f32x4*)(bs + 16384 + (s) * 256); \
;                          X.p = *(const LAS f32x4*)(bs + 24576 + (s) * 256); X.r = *(const LAS f32x4*)(bs + 32768 + (s) * 256); X.v = *(const LAS float*)(bv + (s) * 64); } while (0)
; #define RW_STEP(X, s) do { float sa = fmaf(S[3], X.k[3], fmaf(S[2], X.k[2], fmaf(S[1], X.k[1], S[0] * X.k[0]))); const f32x4 T = S * X.d + X.v * X.p; sa = -red16(sa); \
;                            S = T + sa * X.a; float y = fmaf(S[3], X.r[3], fmaf(S[2], X.r[2], fmaf(S[1], X.r[1], S[0] * X.r[0]))); y = red16(y); \
;                            yk = fmaf(selv[(s) & 15], y, yk); } while (0)
; #define RW_YST(s) do { if ((s) == 15) { ob[(size_t)(rowbase + c * 32 + seg) * D + 512 + h * 64 + vrow] = f2bf(yk); yk = 0.f; } } while (0)
; __device__ __forceinline__ void rwkv_scan(const Params& p, LAS unsigned char* lds, int rowbase, int T, int h, int q4, const float* S0, float* Sout) {
;     ...
;             RwStep xa, xb, xc; float yk = 0.f;
;     ...
;             RW_LD(xa, 0); RW_LD(xb, 1);
; #pragma unroll
;             for (int s = 0; s < 30; s += 3) {
;                 RW_LD(xc, s + 2); RW_STEP(xa, s); RW_YST(s);
;                 RW_LD(xa, s + 3); RW_STEP(xb, s + 1); RW_YST(s + 1);
;                 RW_LD(xb, s + 4); RW_STEP(xc, s + 2); RW_YST(s + 2);
;             }
	v_add_f32_dpp v181, v157, v157 row_mirror row_mask:0xf bank_mask:0xc
	v_pk_mul_f32 v[72:73], v[12:13], v[76:77]
	v_pk_fma_f32 v[72:73], v[14:15], v[78:79], v[72:73]
	ds_read_b128 v[112:115], v2 offset:4864
	v_add_f32_e32 v74, v72, v73
	ds_read_b128 v[120:123], v2 offset:21248
	ds_read_b128 v[116:119], v2 offset:13056
	v_add_f32_dpp v74, v74, v74 quad_perm:[1,0,3,2] row_mask:0xf bank_mask:0xf bound_ctrl:1
	ds_read_b128 v[140:143], v2 offset:29440
	v_pk_fma_f32 v[16:17], v[24:25], v[84:85], v[12:13] op_sel_hi:[0,1,1]
	v_add_f32_dpp v74, v74, v74 quad_perm:[2,3,0,1] row_mask:0xf bank_mask:0xf bound_ctrl:1
	v_pk_fma_f32 v[18:19], v[24:25], v[86:87], v[14:15] op_sel_hi:[0,1,1]
	v_pk_mul_f32 v[198:199], v[12:13], v[124:125]
	v_add_f32_dpp v74, v74, v74 row_half_mirror row_mask:0xf bank_mask:0xf bound_ctrl:1
	v_pk_fma_f32 v[198:199], v[14:15], v[126:127], v[198:199]
	v_add_f32_e32 v159, v198, v199
	v_add_f32_dpp v74, v74, v74 row_mirror row_mask:0xf bank_mask:0xf bound_ctrl:1
	v_pk_fma_f32 v[12:13], v[80:81], v[74:75], v[16:17] op_sel_hi:[1,0,1] neg_lo:[0,1,0] neg_hi:[0,1,0]
	v_pk_fma_f32 v[14:15], v[82:83], v[74:75], v[18:19] op_sel_hi:[1,0,1] neg_lo:[0,1,0] neg_hi:[0,1,0]
	v_add_f32_dpp v185, v181, v181 row_half_mirror row_mask:0xf bank_mask:0xa
	v_add_f32_dpp v182, v150, v150 row_mirror row_mask:0xf bank_mask:0x3
	v_pk_mul_f32 v[72:73], v[12:13], v[88:89]
	v_pk_fma_f32 v[72:73], v[14:15], v[90:91], v[72:73]
	v_add_f32_dpp v182, v158, v158 row_mirror row_mask:0xf bank_mask:0xc
	ds_read_b128 v[76:79], v2 offset:5120
	v_add_f32_e32 v74, v72, v73
	ds_read_b128 v[84:87], v2 offset:21504
	ds_read_b128 v[80:83], v2 offset:13312
	v_add_f32_dpp v74, v74, v74 quad_perm:[1,0,3,2] row_mask:0xf bank_mask:0xf bound_ctrl:1
	ds_read_b128 v[124:127], v2 offset:29696
	ds_read_b128 v[28:31], v3 offset:80
	v_add_f32_dpp v74, v74, v74 quad_perm:[2,3,0,1] row_mask:0xf bank_mask:0xf bound_ctrl:1
	v_pk_fma_f32 v[16:17], v[24:25], v[96:97], v[12:13] op_sel:[1,0,0] op_sel_hi:[1,1,1]
	v_pk_fma_f32 v[18:19], v[24:25], v[98:99], v[14:15] op_sel:[1,0,0] op_sel_hi:[1,1,1]
	v_add_f32_dpp v74, v74, v74 row_half_mirror row_mask:0xf bank_mask:0xf bound_ctrl:1
	v_pk_mul_f32 v[198:199], v[12:13], v[128:129]
	v_pk_fma_f32 v[198:199], v[14:15], v[130:131], v[198:199]
	v_add_f32_dpp v74, v74, v74 row_mirror row_mask:0xf bank_mask:0xf bound_ctrl:1
	v_add_f32_e32 v160, v198, v199
	v_pk_fma_f32 v[12:13], v[92:93], v[74:75], v[16:17] op_sel_hi:[1,0,1] neg_lo:[0,1,0] neg_hi:[0,1,0]
	v_pk_fma_f32 v[14:15], v[94:95], v[74:75], v[18:19] op_sel_hi:[1,0,1] neg_lo:[0,1,0] neg_hi:[0,1,0]
	v_add_f32_dpp v186, v178, v178 row_half_mirror row_mask:0xf bank_mask:0x5
	s_nop 1
	v_add_f32_dpp v186, v182, v182 row_half_mirror row_mask:0xf bank_mask:0xa
	v_cndmask_b32_e64 v190, v184, v186, s[98:99]
	s_waitcnt lgkmcnt(6)
	v_pk_mul_f32 v[72:73], v[12:13], v[100:101]
	v_pk_fma_f32 v[72:73], v[14:15], v[102:103], v[72:73]
	ds_read_b128 v[88:91], v2 offset:5376
	v_add_f32_e32 v74, v72, v73
	ds_read_b128 v[96:99], v2 offset:21760
	ds_read_b128 v[92:95], v2 offset:13568
	v_add_f32_dpp v74, v74, v74 quad_perm:[1,0,3,2] row_mask:0xf bank_mask:0xf bound_ctrl:1
	ds_read_b128 v[128:131], v2 offset:29952
	v_pk_fma_f32 v[16:17], v[26:27], v[108:109], v[12:13] op_sel_hi:[0,1,1]
	v_add_f32_dpp v74, v74, v74 quad_perm:[2,3,0,1] row_mask:0xf bank_mask:0xf bound_ctrl:1
	v_pk_fma_f32 v[18:19], v[26:27], v[110:111], v[14:15] op_sel_hi:[0,1,1]
	v_pk_mul_f32 v[198:199], v[12:13], v[132:133]
	v_add_f32_dpp v74, v74, v74 row_half_mirror row_mask:0xf bank_mask:0xf bound_ctrl:1
	v_pk_fma_f32 v[198:199], v[14:15], v[134:135], v[198:199]
	v_add_f32_e32 v161, v198, v199
	v_add_f32_dpp v74, v74, v74 row_mirror row_mask:0xf bank_mask:0xf bound_ctrl:1
	v_pk_fma_f32 v[12:13], v[104:105], v[74:75], v[16:17] op_sel_hi:[1,0,1] neg_lo:[0,1,0] neg_hi:[0,1,0]
	v_pk_fma_f32 v[14:15], v[106:107], v[74:75], v[18:19] op_sel_hi:[1,0,1] neg_lo:[0,1,0] neg_hi:[0,1,0]
	v_cndmask_b32_e64 v191, v186, v184, s[98:99]
	v_add_f32_dpp v183, v151, v151 row_mirror row_mask:0xf bank_mask:0x3
	v_pk_mul_f32 v[72:73], v[12:13], v[112:113]
	v_add_f32_dpp v188, v191, v190 quad_perm:[2,3,0,1] row_mask:0xf bank_mask:0xf
	v_pk_fma_f32 v[72:73], v[14:15], v[114:115], v[72:73]
	ds_read_b128 v[100:103], v2 offset:5632
	v_add_f32_e32 v74, v72, v73
	ds_read_b128 v[108:111], v2 offset:22016
	ds_read_b128 v[104:107], v2 offset:13824
	v_add_f32_dpp v74, v74, v74 quad_perm:[1,0,3,2] row_mask:0xf bank_mask:0xf bound_ctrl:1
	ds_read_b128 v[132:135], v2 offset:30208
	v_pk_fma_f32 v[16:17], v[26:27], v[120:121], v[12:13] op_sel:[1,0,0] op_sel_hi:[1,1,1]
	v_add_f32_dpp v74, v74, v74 quad_perm:[2,3,0,1] row_mask:0xf bank_mask:0xf bound_ctrl:1
	v_pk_fma_f32 v[18:19], v[26:27], v[122:123], v[14:15] op_sel:[1,0,0] op_sel_hi:[1,1,1]
	v_pk_mul_f32 v[198:199], v[12:13], v[136:137]
	v_add_f32_dpp v74, v74, v74 row_half_mirror row_mask:0xf bank_mask:0xf bound_ctrl:1
	v_pk_fma_f32 v[198:199], v[14:15], v[138:139], v[198:199]
	v_add_f32_e32 v162, v198, v199
	v_add_f32_dpp v74, v74, v74 row_mirror row_mask:0xf bank_mask:0xf bound_ctrl:1
	v_pk_fma_f32 v[12:13], v[116:117], v[74:75], v[16:17] op_sel_hi:[1,0,1] neg_lo:[0,1,0] neg_hi:[0,1,0]
	v_pk_fma_f32 v[14:15], v[118:119], v[74:75], v[18:19] op_sel_hi:[1,0,1] neg_lo:[0,1,0] neg_hi:[0,1,0]
	v_add_f32_dpp v183, v159, v159 row_mirror row_mask:0xf bank_mask:0xc
	v_add_f32_dpp v187, v179, v179 row_half_mirror row_mask:0xf bank_mask:0x5
	s_waitcnt lgkmcnt(5)
; #define RW_LD(X, s) do { X.d = *(const LAS f32x4*)(bs + (s) * 256); X.k = *(const LAS f32x4*)(bs + 8192 + (s) * 256); X.a = *(const LAS f32x4*)(bs + 16384 + (s) * 256); \
;                          X.p = *(const LAS f32x4*)(bs + 24576 + (s) * 256); X.r = *(const LAS f32x4*)(bs + 32768 + (s) * 256); X.v = *(const LAS float*)(bv + (s) * 64); } while (0)
; #define RW_STEP(X, s) do { float sa = fmaf(S[3], X.k[3], fmaf(S[2], X.k[2], fmaf(S[1], X.k[1], S[0] * X.k[0]))); const f32x4 T = S * X.d + X.v * X.p; sa = -red16(sa); \
;                            S = T + sa * X.a; float y = fmaf(S[3], X.r[3], fmaf(S[2], X.r[2], fmaf(S[1], X.r[1], S[0] * X.r[0]))); y = red16(y); \
;                            yk = fmaf(selv[(s) & 15], y, yk); } while (0)
; #define RW_YST(s) do { if ((s) == 15) { ob[(size_t)(rowbase + c * 32 + seg) * D + 512 + h * 64 + vrow] = f2bf(yk); yk = 0.f; } } while (0)
; __device__ __forceinline__ void rwkv_scan(const Params& p, LAS unsigned char* lds, int rowbase, int T, int h, int q4, const float* S0, float* Sout) {
;     ...
;             RwStep xa, xb, xc; float yk = 0.f;
;     ...
;             RW_LD(xa, 0); RW_LD(xb, 1);
; #pragma unroll
;             for (int s = 0; s < 30; s += 3) {
;                 RW_LD(xc, s + 2); RW_STEP(xa, s); RW_YST(s);
;                 RW_LD(xa, s + 3); RW_STEP(xb, s + 1); RW_YST(s + 1);
;                 RW_LD(xb, s + 4); RW_STEP(xc, s + 2); RW_YST(s + 2);
;             }
	v_pk_mul_f32 v[72:73], v[12:13], v[76:77]
	v_add_f32_dpp v187, v183, v183 row_half_mirror row_mask:0xf bank_mask:0xa
	v_pk_fma_f32 v[72:73], v[14:15], v[78:79], v[72:73]
	ds_read_b128 v[112:115], v2 offset:5888
	v_add_f32_e32 v74, v72, v73
	ds_read_b128 v[120:123], v2 offset:22272
	ds_read_b128 v[116:119], v2 offset:14080
	v_add_f32_dpp v74, v74, v74 quad_perm:[1,0,3,2] row_mask:0xf bank_mask:0xf bound_ctrl:1
	ds_read_b128 v[136:139], v2 offset:30464
	v_pk_fma_f32 v[16:17], v[28:29], v[84:85], v[12:13] op_sel_hi:[0,1,1]
	v_add_f32_dpp v74, v74, v74 quad_perm:[2,3,0,1] row_mask:0xf bank_mask:0xf bound_ctrl:1
	v_pk_fma_f32 v[18:19], v[28:29], v[86:87], v[14:15] op_sel_hi:[0,1,1]
	v_pk_mul_f32 v[198:199], v[12:13], v[140:141]
	v_add_f32_dpp v74, v74, v74 row_half_mirror row_mask:0xf bank_mask:0xf bound_ctrl:1
	v_pk_fma_f32 v[198:199], v[14:15], v[142:143], v[198:199]
	v_add_f32_e32 v163, v198, v199
	v_add_f32_dpp v74, v74, v74 row_mirror row_mask:0xf bank_mask:0xf bound_ctrl:1
	v_pk_fma_f32 v[12:13], v[80:81], v[74:75], v[16:17] op_sel_hi:[1,0,1] neg_lo:[0,1,0] neg_hi:[0,1,0]
	v_pk_fma_f32 v[14:15], v[82:83], v[74:75], v[18:19] op_sel_hi:[1,0,1] neg_lo:[0,1,0] neg_hi:[0,1,0]
	v_cndmask_b32_e64 v190, v185, v187, s[98:99]
	v_cndmask_b32_e64 v191, v187, v185, s[98:99]
	v_pk_mul_f32 v[72:73], v[12:13], v[88:89]
	v_pk_fma_f32 v[72:73], v[14:15], v[90:91], v[72:73]
	v_add_f32_dpp v189, v191, v190 quad_perm:[2,3,0,1] row_mask:0xf bank_mask:0xf
	ds_read_b128 v[76:79], v2 offset:6144
	v_add_f32_e32 v74, v72, v73
	ds_read_b128 v[84:87], v2 offset:22528
	ds_read_b128 v[80:83], v2 offset:14336
	v_add_f32_dpp v74, v74, v74 quad_perm:[1,0,3,2] row_mask:0xf bank_mask:0xf bound_ctrl:1
	ds_read_b128 v[140:143], v2 offset:30720
	ds_read_b128 v[24:27], v3 offset:96
	v_add_f32_dpp v74, v74, v74 quad_perm:[2,3,0,1] row_mask:0xf bank_mask:0xf bound_ctrl:1
	v_pk_fma_f32 v[16:17], v[28:29], v[96:97], v[12:13] op_sel:[1,0,0] op_sel_hi:[1,1,1]
	v_pk_fma_f32 v[18:19], v[28:29], v[98:99], v[14:15] op_sel:[1,0,0] op_sel_hi:[1,1,1]
	v_add_f32_dpp v74, v74, v74 row_half_mirror row_mask:0xf bank_mask:0xf bound_ctrl:1
	v_pk_mul_f32 v[198:199], v[12:13], v[124:125]
	v_pk_fma_f32 v[198:199], v[14:15], v[126:127], v[198:199]
	v_add_f32_dpp v74, v74, v74 row_mirror row_mask:0xf bank_mask:0xf bound_ctrl:1
	v_add_f32_e32 v164, v198, v199
	v_pk_fma_f32 v[12:13], v[92:93], v[74:75], v[16:17] op_sel_hi:[1,0,1] neg_lo:[0,1,0] neg_hi:[0,1,0]
	v_pk_fma_f32 v[14:15], v[94:95], v[74:75], v[18:19] op_sel_hi:[1,0,1] neg_lo:[0,1,0] neg_hi:[0,1,0]
	v_cndmask_b32_e64 v190, v188, v189, s[100:101]
	v_cndmask_b32_e64 v191, v189, v188, s[100:101]
	s_waitcnt lgkmcnt(6)
	v_pk_mul_f32 v[72:73], v[12:13], v[100:101]
	v_add_f32_dpp v192, v191, v190 quad_perm:[1,0,3,2] row_mask:0xf bank_mask:0xf
	v_pk_fma_f32 v[72:73], v[14:15], v[102:103], v[72:73]
	ds_read_b128 v[88:91], v2 offset:6400
	v_add_f32_e32 v74, v72, v73
	ds_read_b128 v[96:99], v2 offset:22784
	ds_read_b128 v[92:95], v2 offset:14592
	v_add_f32_dpp v74, v74, v74 quad_perm:[1,0,3,2] row_mask:0xf bank_mask:0xf bound_ctrl:1
	ds_read_b128 v[124:127], v2 offset:30976
	v_pk_fma_f32 v[16:17], v[30:31], v[108:109], v[12:13] op_sel_hi:[0,1,1]
	v_add_f32_dpp v74, v74, v74 quad_perm:[2,3,0,1] row_mask:0xf bank_mask:0xf bound_ctrl:1
	v_pk_fma_f32 v[18:19], v[30:31], v[110:111], v[14:15] op_sel_hi:[0,1,1]
	v_pk_mul_f32 v[198:199], v[12:13], v[128:129]
	v_add_f32_dpp v74, v74, v74 row_half_mirror row_mask:0xf bank_mask:0xf bound_ctrl:1
	v_pk_fma_f32 v[198:199], v[14:15], v[130:131], v[198:199]
	v_add_f32_e32 v165, v198, v199
	v_add_f32_dpp v74, v74, v74 row_mirror row_mask:0xf bank_mask:0xf bound_ctrl:1
	v_pk_fma_f32 v[12:13], v[104:105], v[74:75], v[16:17] op_sel_hi:[1,0,1] neg_lo:[0,1,0] neg_hi:[0,1,0]
	v_pk_fma_f32 v[14:15], v[106:107], v[74:75], v[18:19] op_sel_hi:[1,0,1] neg_lo:[0,1,0] neg_hi:[0,1,0]
	v_lshlrev_b32_e32 v194, 11, v5
	v_mov_b32_e32 v195, 0
	v_pk_mul_f32 v[72:73], v[12:13], v[112:113]
	v_pk_fma_f32 v[72:73], v[14:15], v[114:115], v[72:73]
	ds_read_b128 v[100:103], v2 offset:6656
	v_add_f32_e32 v74, v72, v73
	ds_read_b128 v[108:111], v2 offset:23040
	ds_read_b128 v[104:107], v2 offset:14848
	v_add_f32_dpp v74, v74, v74 quad_perm:[1,0,3,2] row_mask:0xf bank_mask:0xf bound_ctrl:1
	ds_read_b128 v[128:131], v2 offset:31232
	v_pk_fma_f32 v[16:17], v[30:31], v[120:121], v[12:13] op_sel:[1,0,0] op_sel_hi:[1,1,1]
	v_add_f32_dpp v74, v74, v74 quad_perm:[2,3,0,1] row_mask:0xf bank_mask:0xf bound_ctrl:1
	v_pk_fma_f32 v[18:19], v[30:31], v[122:123], v[14:15] op_sel:[1,0,0] op_sel_hi:[1,1,1]
	v_pk_mul_f32 v[198:199], v[12:13], v[132:133]
	v_add_f32_dpp v74, v74, v74 row_half_mirror row_mask:0xf bank_mask:0xf bound_ctrl:1
	v_pk_fma_f32 v[198:199], v[14:15], v[134:135], v[198:199]
	v_add_f32_e32 v166, v198, v199
	v_add_f32_dpp v74, v74, v74 row_mirror row_mask:0xf bank_mask:0xf bound_ctrl:1
	v_pk_fma_f32 v[12:13], v[116:117], v[74:75], v[16:17] op_sel_hi:[1,0,1] neg_lo:[0,1,0] neg_hi:[0,1,0]
	v_pk_fma_f32 v[14:15], v[118:119], v[74:75], v[18:19] op_sel_hi:[1,0,1] neg_lo:[0,1,0] neg_hi:[0,1,0]
	v_cvt_pk_bf16_f32 v193, v192, v192
	v_lshl_add_u64 v[194:195], v[6:7], 0, v[194:195]
	s_waitcnt lgkmcnt(5)
; #define RW_LD(X, s) do { X.d = *(const LAS f32x4*)(bs + (s) * 256); X.k = *(const LAS f32x4*)(bs + 8192 + (s) * 256); X.a = *(const LAS f32x4*)(bs + 16384 + (s) * 256); \
;                          X.p = *(const LAS f32x4*)(bs + 24576 + (s) * 256); X.r = *(const LAS f32x4*)(bs + 32768 + (s) * 256); X.v = *(const LAS float*)(bv + (s) * 64); } while (0)
; #define RW_STEP(X, s) do { float sa = fmaf(S[3], X.k[3], fmaf(S[2], X.k[2], fmaf(S[1], X.k[1], S[0] * X.k[0]))); const f32x4 T = S * X.d + X.v * X.p; sa = -red16(sa); \
;                            S = T + sa * X.a; float y = fmaf(S[3], X.r[3], fmaf(S[2], X.r[2], fmaf(S[1], X.r[1], S[0] * X.r[0]))); y = red16(y); \
;                            yk = fmaf(selv[(s) & 15], y, yk); } while (0)
; #define RW_YST(s) do { if ((s) == 15) { ob[(size_t)(rowbase + c * 32 + seg) * D + 512 + h * 64 + vrow] = f2bf(yk); yk = 0.f; } } while (0)
; __device__ __forceinline__ void rwkv_scan(const Params& p, LAS unsigned char* lds, int rowbase, int T, int h, int q4, const float* S0, float* Sout) {
;     ...
;             RwStep xa, xb, xc; float yk = 0.f;
;     ...
;             RW_LD(xa, 0); RW_LD(xb, 1);
; #pragma unroll
;             for (int s = 0; s < 30; s += 3) {
;                 RW_LD(xc, s + 2); RW_STEP(xa, s); RW_YST(s);
;                 RW_LD(xa, s + 3); RW_STEP(xb, s + 1); RW_YST(s + 1);
;                 RW_LD(xb, s + 4); RW_STEP(xc, s + 2); RW_YST(s + 2);
;             }
	v_pk_mul_f32 v[72:73], v[12:13], v[76:77]
	v_pk_fma_f32 v[72:73], v[14:15], v[78:79], v[72:73]
	ds_read_b128 v[112:115], v2 offset:6912
	v_add_f32_e32 v74, v72, v73
	ds_read_b128 v[120:123], v2 offset:23296
	ds_read_b128 v[116:119], v2 offset:15104
	v_add_f32_dpp v74, v74, v74 quad_perm:[1,0,3,2] row_mask:0xf bank_mask:0xf bound_ctrl:1
	ds_read_b128 v[132:135], v2 offset:31488
	v_pk_fma_f32 v[16:17], v[24:25], v[84:85], v[12:13] op_sel_hi:[0,1,1]
	v_add_f32_dpp v74, v74, v74 quad_perm:[2,3,0,1] row_mask:0xf bank_mask:0xf bound_ctrl:1
	v_pk_fma_f32 v[18:19], v[24:25], v[86:87], v[14:15] op_sel_hi:[0,1,1]
	v_pk_mul_f32 v[198:199], v[12:13], v[136:137]
	v_add_f32_dpp v74, v74, v74 row_half_mirror row_mask:0xf bank_mask:0xf bound_ctrl:1
	v_pk_fma_f32 v[198:199], v[14:15], v[138:139], v[198:199]
	v_add_f32_e32 v167, v198, v199
	v_add_f32_dpp v74, v74, v74 row_mirror row_mask:0xf bank_mask:0xf bound_ctrl:1
	v_pk_fma_f32 v[12:13], v[80:81], v[74:75], v[16:17] op_sel_hi:[1,0,1] neg_lo:[0,1,0] neg_hi:[0,1,0]
	v_pk_fma_f32 v[14:15], v[82:83], v[74:75], v[18:19] op_sel_hi:[1,0,1] neg_lo:[0,1,0] neg_hi:[0,1,0]
	global_store_short v[194:195], v193, off offset:1024
	v_pk_mul_f32 v[72:73], v[12:13], v[88:89]
	v_pk_fma_f32 v[72:73], v[14:15], v[90:91], v[72:73]
	ds_read_b128 v[76:79], v2 offset:7168
	v_add_f32_e32 v74, v72, v73
	ds_read_b128 v[84:87], v2 offset:23552
	ds_read_b128 v[80:83], v2 offset:15360
	v_add_f32_dpp v74, v74, v74 quad_perm:[1,0,3,2] row_mask:0xf bank_mask:0xf bound_ctrl:1
	ds_read_b128 v[136:139], v2 offset:31744
	ds_read_b128 v[28:31], v3 offset:112
	v_add_f32_dpp v74, v74, v74 quad_perm:[2,3,0,1] row_mask:0xf bank_mask:0xf bound_ctrl:1
	v_pk_fma_f32 v[16:17], v[24:25], v[96:97], v[12:13] op_sel:[1,0,0] op_sel_hi:[1,1,1]
	v_pk_fma_f32 v[18:19], v[24:25], v[98:99], v[14:15] op_sel:[1,0,0] op_sel_hi:[1,1,1]
	v_add_f32_dpp v74, v74, v74 row_half_mirror row_mask:0xf bank_mask:0xf bound_ctrl:1
	v_pk_mul_f32 v[198:199], v[12:13], v[140:141]
	v_pk_fma_f32 v[198:199], v[14:15], v[142:143], v[198:199]
	v_add_f32_dpp v74, v74, v74 row_mirror row_mask:0xf bank_mask:0xf bound_ctrl:1
	v_add_f32_e32 v168, v198, v199
	v_pk_fma_f32 v[12:13], v[92:93], v[74:75], v[16:17] op_sel_hi:[1,0,1] neg_lo:[0,1,0] neg_hi:[0,1,0]
	v_pk_fma_f32 v[14:15], v[94:95], v[74:75], v[18:19] op_sel_hi:[1,0,1] neg_lo:[0,1,0] neg_hi:[0,1,0]
	v_add_f32_dpp v176, v160, v160 row_mirror row_mask:0xf bank_mask:0x3
	s_waitcnt lgkmcnt(6)
	v_pk_mul_f32 v[72:73], v[12:13], v[100:101]
	v_add_f32_dpp v176, v168, v168 row_mirror row_mask:0xf bank_mask:0xc
	v_pk_fma_f32 v[72:73], v[14:15], v[102:103], v[72:73]
	ds_read_b128 v[88:91], v2 offset:7424
	v_add_f32_e32 v74, v72, v73
	ds_read_b128 v[96:99], v2 offset:23808
	ds_read_b128 v[92:95], v2 offset:15616
	v_add_f32_dpp v74, v74, v74 quad_perm:[1,0,3,2] row_mask:0xf bank_mask:0xf bound_ctrl:1
	ds_read_b128 v[140:143], v2 offset:32000
	v_pk_fma_f32 v[16:17], v[26:27], v[108:109], v[12:13] op_sel_hi:[0,1,1]
	v_add_f32_dpp v74, v74, v74 quad_perm:[2,3,0,1] row_mask:0xf bank_mask:0xf bound_ctrl:1
	v_pk_fma_f32 v[18:19], v[26:27], v[110:111], v[14:15] op_sel_hi:[0,1,1]
	v_pk_mul_f32 v[198:199], v[12:13], v[124:125]
	v_add_f32_dpp v74, v74, v74 row_half_mirror row_mask:0xf bank_mask:0xf bound_ctrl:1
	v_pk_fma_f32 v[198:199], v[14:15], v[126:127], v[198:199]
	v_add_f32_e32 v169, v198, v199
	v_add_f32_dpp v74, v74, v74 row_mirror row_mask:0xf bank_mask:0xf bound_ctrl:1
	v_pk_fma_f32 v[12:13], v[104:105], v[74:75], v[16:17] op_sel_hi:[1,0,1] neg_lo:[0,1,0] neg_hi:[0,1,0]
	v_pk_fma_f32 v[14:15], v[106:107], v[74:75], v[18:19] op_sel_hi:[1,0,1] neg_lo:[0,1,0] neg_hi:[0,1,0]
	v_add_f32_dpp v177, v161, v161 row_mirror row_mask:0xf bank_mask:0x3
	v_pk_mul_f32 v[72:73], v[12:13], v[112:113]
	v_pk_fma_f32 v[72:73], v[14:15], v[114:115], v[72:73]
	v_add_f32_dpp v177, v169, v169 row_mirror row_mask:0xf bank_mask:0xc
	ds_read_b128 v[100:103], v2 offset:7680
	v_add_f32_e32 v74, v72, v73
	ds_read_b128 v[108:111], v2 offset:24064
	ds_read_b128 v[104:107], v2 offset:15872
	v_add_f32_dpp v74, v74, v74 quad_perm:[1,0,3,2] row_mask:0xf bank_mask:0xf bound_ctrl:1
	ds_read_b128 v[124:127], v2 offset:32256
	v_pk_fma_f32 v[16:17], v[26:27], v[120:121], v[12:13] op_sel:[1,0,0] op_sel_hi:[1,1,1]
	v_add_f32_dpp v74, v74, v74 quad_perm:[2,3,0,1] row_mask:0xf bank_mask:0xf bound_ctrl:1
	v_pk_fma_f32 v[18:19], v[26:27], v[122:123], v[14:15] op_sel:[1,0,0] op_sel_hi:[1,1,1]
	v_pk_mul_f32 v[198:199], v[12:13], v[128:129]
	v_add_f32_dpp v74, v74, v74 row_half_mirror row_mask:0xf bank_mask:0xf bound_ctrl:1
	v_pk_fma_f32 v[198:199], v[14:15], v[130:131], v[198:199]
	v_add_f32_e32 v170, v198, v199
	v_add_f32_dpp v74, v74, v74 row_mirror row_mask:0xf bank_mask:0xf bound_ctrl:1
	v_pk_fma_f32 v[12:13], v[116:117], v[74:75], v[16:17] op_sel_hi:[1,0,1] neg_lo:[0,1,0] neg_hi:[0,1,0]
	v_pk_fma_f32 v[14:15], v[118:119], v[74:75], v[18:19] op_sel_hi:[1,0,1] neg_lo:[0,1,0] neg_hi:[0,1,0]
	v_add_f32_dpp v178, v162, v162 row_mirror row_mask:0xf bank_mask:0x3
	s_waitcnt lgkmcnt(5)
; __device__ __forceinline__ bf16_t f2bf(float f) { return (bf16_t)(cvt_pk_bf16(f, 0.f) & 0xffffu); }
; #define RW_LD(X, s) do { X.d = *(const LAS f32x4*)(bs + (s) * 256); X.k = *(const LAS f32x4*)(bs + 8192 + (s) * 256); X.a = *(const LAS f32x4*)(bs + 16384 + (s) * 256); \
;                          X.p = *(const LAS f32x4*)(bs + 24576 + (s) * 256); X.r = *(const LAS f32x4*)(bs + 32768 + (s) * 256); X.v = *(const LAS float*)(bv + (s) * 64); } while (0)
; #define RW_STEP(X, s) do { float sa = fmaf(S[3], X.k[3], fmaf(S[2], X.k[2], fmaf(S[1], X.k[1], S[0] * X.k[0]))); const f32x4 T = S * X.d + X.v * X.p; sa = -red16(sa); \
;                            S = T + sa * X.a; float y = fmaf(S[3], X.r[3], fmaf(S[2], X.r[2], fmaf(S[1], X.r[1], S[0] * X.r[0]))); y = red16(y); \
;                            yk = fmaf(selv[(s) & 15], y, yk); } while (0)
; #define RW_YST(s) do { if ((s) == 15) { ob[(size_t)(rowbase + c * 32 + seg) * D + 512 + h * 64 + vrow] = f2bf(yk); yk = 0.f; } } while (0)
; __device__ __forceinline__ void rwkv_scan(const Params& p, LAS unsigned char* lds, int rowbase, int T, int h, int q4, const float* S0, float* Sout) {
;     ...
;             RwStep xa, xb, xc; float yk = 0.f;
;     ...
;             RW_LD(xa, 0); RW_LD(xb, 1);
; #pragma unroll
;             for (int s = 0; s < 30; s += 3) {
;                 RW_LD(xc, s + 2); RW_STEP(xa, s); RW_YST(s);
;                 RW_LD(xa, s + 3); RW_STEP(xb, s + 1); RW_YST(s + 1);
;                 RW_LD(xb, s + 4); RW_STEP(xc, s + 2); RW_YST(s + 2);
;             }
;             RW_STEP(xa, 30); RW_STEP(xb, 31);
;             ob[(size_t)(rowbase + c * 32 + 16 + seg) * D + 512 + h * 64 + vrow] = f2bf(yk);
;     ...
;         }
;     }
;     if (comp) *(f32x4*)(Sout + vrow * 64 + seg * 4) = S;
;     __syncthreads();
	v_pk_mul_f32 v[72:73], v[12:13], v[76:77]
	v_add_f32_dpp v178, v170, v170 row_mirror row_mask:0xf bank_mask:0xc
	v_pk_fma_f32 v[72:73], v[14:15], v[78:79], v[72:73]
	ds_read_b128 v[112:115], v2 offset:7936
	v_add_f32_e32 v74, v72, v73
	ds_read_b128 v[120:123], v2 offset:24320
	ds_read_b128 v[116:119], v2 offset:16128
	v_add_f32_dpp v74, v74, v74 quad_perm:[1,0,3,2] row_mask:0xf bank_mask:0xf bound_ctrl:1
	ds_read_b128 v[128:131], v2 offset:32512
	v_pk_fma_f32 v[16:17], v[28:29], v[84:85], v[12:13] op_sel_hi:[0,1,1]
	v_add_f32_dpp v74, v74, v74 quad_perm:[2,3,0,1] row_mask:0xf bank_mask:0xf bound_ctrl:1
	v_pk_fma_f32 v[18:19], v[28:29], v[86:87], v[14:15] op_sel_hi:[0,1,1]
	v_pk_mul_f32 v[198:199], v[12:13], v[132:133]
	v_add_f32_dpp v74, v74, v74 row_half_mirror row_mask:0xf bank_mask:0xf bound_ctrl:1
	v_pk_fma_f32 v[198:199], v[14:15], v[134:135], v[198:199]
	v_add_f32_e32 v171, v198, v199
	v_add_f32_dpp v74, v74, v74 row_mirror row_mask:0xf bank_mask:0xf bound_ctrl:1
	v_pk_fma_f32 v[12:13], v[80:81], v[74:75], v[16:17] op_sel_hi:[1,0,1] neg_lo:[0,1,0] neg_hi:[0,1,0]
	v_pk_fma_f32 v[14:15], v[82:83], v[74:75], v[18:19] op_sel_hi:[1,0,1] neg_lo:[0,1,0] neg_hi:[0,1,0]
	v_add_f32_dpp v179, v163, v163 row_mirror row_mask:0xf bank_mask:0x3
	v_pk_mul_f32 v[72:73], v[12:13], v[88:89]
	v_pk_fma_f32 v[72:73], v[14:15], v[90:91], v[72:73]
	v_add_f32_dpp v179, v171, v171 row_mirror row_mask:0xf bank_mask:0xc
	v_pk_fma_f32 v[16:17], v[28:29], v[96:97], v[12:13] op_sel:[1,0,0] op_sel_hi:[1,1,1]
	v_add_f32_e32 v74, v72, v73
	v_pk_fma_f32 v[18:19], v[28:29], v[98:99], v[14:15] op_sel:[1,0,0] op_sel_hi:[1,1,1]
	v_pk_mul_f32 v[198:199], v[12:13], v[136:137]
	v_add_f32_dpp v74, v74, v74 quad_perm:[1,0,3,2] row_mask:0xf bank_mask:0xf bound_ctrl:1
	v_pk_fma_f32 v[198:199], v[14:15], v[138:139], v[198:199]
	v_add_f32_e32 v172, v198, v199
	v_add_f32_dpp v74, v74, v74 quad_perm:[2,3,0,1] row_mask:0xf bank_mask:0xf bound_ctrl:1
	v_add_f32_dpp v180, v164, v164 row_mirror row_mask:0xf bank_mask:0x3
	s_nop 1
	v_add_f32_dpp v180, v172, v172 row_mirror row_mask:0xf bank_mask:0xc
	v_add_f32_dpp v74, v74, v74 row_half_mirror row_mask:0xf bank_mask:0xf bound_ctrl:1
	s_nop 1
	v_add_f32_dpp v74, v74, v74 row_mirror row_mask:0xf bank_mask:0xf bound_ctrl:1
	v_pk_fma_f32 v[12:13], v[92:93], v[74:75], v[16:17] op_sel_hi:[1,0,1] neg_lo:[0,1,0] neg_hi:[0,1,0]
	v_pk_fma_f32 v[14:15], v[94:95], v[74:75], v[18:19] op_sel_hi:[1,0,1] neg_lo:[0,1,0] neg_hi:[0,1,0]
	s_waitcnt lgkmcnt(0)
	v_pk_mul_f32 v[72:73], v[12:13], v[100:101]
	v_pk_fma_f32 v[72:73], v[14:15], v[102:103], v[72:73]
	v_pk_fma_f32 v[16:17], v[30:31], v[108:109], v[12:13] op_sel_hi:[0,1,1]
	v_add_f32_e32 v74, v72, v73
	v_pk_fma_f32 v[18:19], v[30:31], v[110:111], v[14:15] op_sel_hi:[0,1,1]
	v_pk_mul_f32 v[198:199], v[12:13], v[140:141]
	v_add_f32_dpp v74, v74, v74 quad_perm:[1,0,3,2] row_mask:0xf bank_mask:0xf bound_ctrl:1
	v_pk_fma_f32 v[198:199], v[14:15], v[142:143], v[198:199]
	v_add_f32_e32 v173, v198, v199
	v_add_f32_dpp v74, v74, v74 quad_perm:[2,3,0,1] row_mask:0xf bank_mask:0xf bound_ctrl:1
	v_add_f32_dpp v184, v176, v176 row_half_mirror row_mask:0xf bank_mask:0x5
	s_nop 1
	v_add_f32_dpp v184, v180, v180 row_half_mirror row_mask:0xf bank_mask:0xa
	v_add_f32_dpp v74, v74, v74 row_half_mirror row_mask:0xf bank_mask:0xf bound_ctrl:1
	s_nop 1
	v_add_f32_dpp v74, v74, v74 row_mirror row_mask:0xf bank_mask:0xf bound_ctrl:1
	v_pk_fma_f32 v[12:13], v[104:105], v[74:75], v[16:17] op_sel_hi:[1,0,1] neg_lo:[0,1,0] neg_hi:[0,1,0]
	v_pk_fma_f32 v[14:15], v[106:107], v[74:75], v[18:19] op_sel_hi:[1,0,1] neg_lo:[0,1,0] neg_hi:[0,1,0]
	v_pk_mul_f32 v[72:73], v[12:13], v[112:113]
	v_pk_fma_f32 v[72:73], v[14:15], v[114:115], v[72:73]
	v_pk_fma_f32 v[16:17], v[30:31], v[120:121], v[12:13] op_sel:[1,0,0] op_sel_hi:[1,1,1]
	v_add_f32_e32 v74, v72, v73
	v_pk_fma_f32 v[18:19], v[30:31], v[122:123], v[14:15] op_sel:[1,0,0] op_sel_hi:[1,1,1]
	v_pk_mul_f32 v[198:199], v[12:13], v[124:125]
	v_add_f32_dpp v74, v74, v74 quad_perm:[1,0,3,2] row_mask:0xf bank_mask:0xf bound_ctrl:1
	v_pk_fma_f32 v[198:199], v[14:15], v[126:127], v[198:199]
	v_add_f32_e32 v174, v198, v199
	v_add_f32_dpp v74, v74, v74 quad_perm:[2,3,0,1] row_mask:0xf bank_mask:0xf bound_ctrl:1
	v_add_f32_dpp v181, v165, v165 row_mirror row_mask:0xf bank_mask:0x3
	v_add_f32_dpp v185, v177, v177 row_half_mirror row_mask:0xf bank_mask:0x5
	v_add_f32_dpp v74, v74, v74 row_half_mirror row_mask:0xf bank_mask:0xf bound_ctrl:1
	v_add_f32_dpp v181, v173, v173 row_mirror row_mask:0xf bank_mask:0xc
	s_nop 0
	v_add_f32_dpp v74, v74, v74 row_mirror row_mask:0xf bank_mask:0xf bound_ctrl:1
	v_pk_fma_f32 v[12:13], v[116:117], v[74:75], v[16:17] op_sel_hi:[1,0,1] neg_lo:[0,1,0] neg_hi:[0,1,0]
	v_pk_fma_f32 v[14:15], v[118:119], v[74:75], v[18:19] op_sel_hi:[1,0,1] neg_lo:[0,1,0] neg_hi:[0,1,0]
	ds_read_b128 v[20:23], v4
	v_pk_mul_f32 v[198:199], v[12:13], v[128:129]
	v_pk_fma_f32 v[198:199], v[14:15], v[130:131], v[198:199]
	v_add_f32_e32 v175, v198, v199
	v_add_f32_dpp v185, v181, v181 row_half_mirror row_mask:0xf bank_mask:0xa
	v_add_f32_dpp v182, v166, v166 row_mirror row_mask:0xf bank_mask:0x3
	s_nop 1
	v_add_f32_dpp v182, v174, v174 row_mirror row_mask:0xf bank_mask:0xc
	v_add_f32_dpp v186, v178, v178 row_half_mirror row_mask:0xf bank_mask:0x5
	s_nop 1
	v_add_f32_dpp v186, v182, v182 row_half_mirror row_mask:0xf bank_mask:0xa
	v_cndmask_b32_e64 v190, v184, v186, s[98:99]
	v_cndmask_b32_e64 v191, v186, v184, s[98:99]
	v_add_f32_dpp v183, v167, v167 row_mirror row_mask:0xf bank_mask:0x3
	v_add_f32_dpp v187, v179, v179 row_half_mirror row_mask:0xf bank_mask:0x5
	v_add_f32_dpp v188, v191, v190 quad_perm:[2,3,0,1] row_mask:0xf bank_mask:0xf
	s_waitcnt lgkmcnt(0)
	v_add_f32_dpp v183, v175, v175 row_mirror row_mask:0xf bank_mask:0xc
	v_pk_mul_f32 v[12:13], v[12:13], v[20:21]
	v_pk_mul_f32 v[14:15], v[14:15], v[22:23]
	v_add_f32_dpp v187, v183, v183 row_half_mirror row_mask:0xf bank_mask:0xa
	v_cndmask_b32_e64 v190, v185, v187, s[98:99]
	v_cndmask_b32_e64 v191, v187, v185, s[98:99]
	s_nop 1
	v_add_f32_dpp v189, v191, v190 quad_perm:[2,3,0,1] row_mask:0xf bank_mask:0xf
	v_cndmask_b32_e64 v190, v188, v189, s[100:101]
	v_cndmask_b32_e64 v191, v189, v188, s[100:101]
	v_add_u32_e32 v196, 16, v5
	v_lshlrev_b32_e32 v194, 11, v196
	v_add_f32_dpp v192, v191, v190 quad_perm:[1,0,3,2] row_mask:0xf bank_mask:0xf
	v_mov_b32_e32 v195, 0
	v_cvt_pk_bf16_f32 v193, v192, v192
	v_lshl_add_u64 v[194:195], v[6:7], 0, v[194:195]
	global_store_short v[194:195], v193, off offset:1024
	v_add_u32_e32 v5, 32, v5
	s_bitcmp1_b32 s22, 0
	s_cselect_b32 s4, s39, s38
	v_add_u32_e32 v2, s4, v2
	v_add_u32_e32 v3, s4, v3
	v_add_u32_e32 v4, s4, v4
	s_add_i32 s22, s22, 1
	s_cmpk_lt_i32 s22, 128
	s_cbranch_scc1 .Lrw3_cloop
	global_store_dwordx4 v[8:9], v[12:15], off
	s_setprio 0
	s_branch .LBB0_738
